# hand-written EpiResid epilogue for gemm_out and gemm_down: batched loads then fma+stores
# speedup vs baseline: 1.0432x; 1.0432x over previous
.LBB0_1578:
	s_add_i32 s42, s42, 1
	s_mov_b64 s[0:1], 0
	s_barrier

.LBB0_1595:
	s_waitcnt vmcnt(0)
	s_lshl_b32 s6, s40, 19
	s_lshl_b32 s7, s38, 9
	v_readfirstlane_b32 s2, v134
	v_readfirstlane_b32 s3, v135
	v_readlane_b32 s0, v255, 9
	s_add_u32 s8, s2, s56
	s_addc_u32 s9, s3, s57
	s_add_u32 s8, s8, s6
	s_addc_u32 s9, s9, 0
	s_add_u32 s8, s8, s7
	s_addc_u32 s9, s9, 0
	s_mov_b64 s[10:11], s[8:9]
	s_cmp_lg_u32 s0, 0
	s_cbranch_scc1 .Lgo_src_done
	s_cmp_lt_u32 s40, 32
	s_cbranch_scc0 .Lgo_src_xs
	v_readfirstlane_b32 s10, v64
	v_readfirstlane_b32 s11, v65
	s_add_u32 s10, s10, s6
	s_addc_u32 s11, s11, 0
	s_branch .Lgo_src_addn
.Lgo_src_xs:
	v_readfirstlane_b32 s10, v66
	v_readfirstlane_b32 s11, v67
	s_sub_u32 s1, s6, 0x1000000
	s_add_u32 s10, s10, s1
	s_addc_u32 s11, s11, 0
.Lgo_src_addn:
	s_add_u32 s10, s10, s7
	s_addc_u32 s11, s11, 0
.Lgo_src_done:
	s_mul_i32 s12, s0, 0x12000
	s_add_u32 s12, s12, 0x2a22000
	s_sub_u32 s1, s40, 16
	s_lshr_b32 s1, s1, 4
	s_cmp_lt_u32 s40, 32
	s_cselect_b32 s1, 0, s1
	s_mul_i32 s1, s1, 0x6000
	s_add_u32 s12, s12, s1
	s_add_u32 s12, s12, s7
	s_add_u32 s12, s2, s12
	s_addc_u32 s13, s3, 0
	v_and_b32_e32 v64, 31, v231
	v_bfe_u32 v65, v231, 6, 1
	v_lshl_or_b32 v65, v65, 6, v64
	v_lshlrev_b32_e32 v65, 2, v65
	v_bfe_u32 v64, v231, 5, 1
	v_bfe_u32 v66, v231, 7, 1
	v_lshl_or_b32 v64, v66, 4, v64
	v_lshl_or_b32 v64, v64, 14, v65
	global_load_dword v66, v65, s[12:13]
	global_load_dword v67, v65, s[12:13] offset:128
	s_add_u32 s14, s10, 0x1000
	s_addc_u32 s15, s11, 0
	global_load_dword v68, v64, s[14:15] offset:-4096
	global_load_dword v69, v64, s[14:15] offset:-3968
	global_load_dword v70, v64, s[14:15]
	global_load_dword v71, v64, s[14:15] offset:128
	s_add_u32 s14, s10, 0x3000
	s_addc_u32 s15, s11, 0
	global_load_dword v72, v64, s[14:15] offset:-4096
	global_load_dword v73, v64, s[14:15] offset:-3968
	global_load_dword v74, v64, s[14:15]
	global_load_dword v75, v64, s[14:15] offset:128
	s_add_u32 s14, s10, 0x9000
	s_addc_u32 s15, s11, 0
	global_load_dword v76, v64, s[14:15] offset:-4096
	global_load_dword v77, v64, s[14:15] offset:-3968
	global_load_dword v78, v64, s[14:15]
	global_load_dword v79, v64, s[14:15] offset:128
	s_add_u32 s14, s10, 0xb000
	s_addc_u32 s15, s11, 0
	global_load_dword v80, v64, s[14:15] offset:-4096
	global_load_dword v81, v64, s[14:15] offset:-3968
	global_load_dword v82, v64, s[14:15]
	global_load_dword v83, v64, s[14:15] offset:128
	s_add_u32 s14, s10, 0x11000
	s_addc_u32 s15, s11, 0
	global_load_dword v84, v64, s[14:15] offset:-4096
	global_load_dword v85, v64, s[14:15] offset:-3968
	global_load_dword v86, v64, s[14:15]
	global_load_dword v87, v64, s[14:15] offset:128
	s_add_u32 s14, s10, 0x13000
	s_addc_u32 s15, s11, 0
	global_load_dword v88, v64, s[14:15] offset:-4096
	global_load_dword v89, v64, s[14:15] offset:-3968
	global_load_dword v90, v64, s[14:15]
	global_load_dword v91, v64, s[14:15] offset:128
	s_add_u32 s14, s10, 0x19000
	s_addc_u32 s15, s11, 0
	global_load_dword v92, v64, s[14:15] offset:-4096
	global_load_dword v93, v64, s[14:15] offset:-3968
	global_load_dword v94, v64, s[14:15]
	global_load_dword v95, v64, s[14:15] offset:128
	s_add_u32 s14, s10, 0x1b000
	s_addc_u32 s15, s11, 0
	global_load_dword v96, v64, s[14:15] offset:-4096
	global_load_dword v97, v64, s[14:15] offset:-3968
	global_load_dword v98, v64, s[14:15]
	global_load_dword v99, v64, s[14:15] offset:128
	s_add_u32 s14, s10, 0x21000
	s_addc_u32 s15, s11, 0
	global_load_dword v100, v64, s[14:15] offset:-4096
	global_load_dword v101, v64, s[14:15] offset:-3968
	global_load_dword v102, v64, s[14:15]
	global_load_dword v103, v64, s[14:15] offset:128
	s_add_u32 s14, s10, 0x23000
	s_addc_u32 s15, s11, 0
	global_load_dword v104, v64, s[14:15] offset:-4096
	global_load_dword v105, v64, s[14:15] offset:-3968
	global_load_dword v106, v64, s[14:15]
	global_load_dword v107, v64, s[14:15] offset:128
	s_add_u32 s14, s10, 0x29000
	s_addc_u32 s15, s11, 0
	global_load_dword v108, v64, s[14:15] offset:-4096
	global_load_dword v109, v64, s[14:15] offset:-3968
	global_load_dword v110, v64, s[14:15]
	global_load_dword v111, v64, s[14:15] offset:128
	s_add_u32 s14, s10, 0x2b000
	s_addc_u32 s15, s11, 0
	global_load_dword v112, v64, s[14:15] offset:-4096
	global_load_dword v113, v64, s[14:15] offset:-3968
	global_load_dword v114, v64, s[14:15]
	global_load_dword v115, v64, s[14:15] offset:128
	s_add_u32 s14, s10, 0x31000
	s_addc_u32 s15, s11, 0
	global_load_dword v116, v64, s[14:15] offset:-4096
	global_load_dword v117, v64, s[14:15] offset:-3968
	global_load_dword v118, v64, s[14:15]
	global_load_dword v119, v64, s[14:15] offset:128
	s_add_u32 s14, s10, 0x33000
	s_addc_u32 s15, s11, 0
	global_load_dword v120, v64, s[14:15] offset:-4096
	global_load_dword v121, v64, s[14:15] offset:-3968
	global_load_dword v122, v64, s[14:15]
	global_load_dword v123, v64, s[14:15] offset:128
	s_add_u32 s14, s10, 0x39000
	s_addc_u32 s15, s11, 0
	global_load_dword v124, v64, s[14:15] offset:-4096
	global_load_dword v125, v64, s[14:15] offset:-3968
	global_load_dword v126, v64, s[14:15]
	global_load_dword v127, v64, s[14:15] offset:128
	s_add_u32 s14, s10, 0x3b000
	s_addc_u32 s15, s11, 0
	global_load_dword v128, v64, s[14:15] offset:-4096
	global_load_dword v129, v64, s[14:15] offset:-3968
	global_load_dword v130, v64, s[14:15]
	global_load_dword v131, v64, s[14:15] offset:128
	s_waitcnt vmcnt(32)
	v_fmac_f32_e32 v68, v66, v48
	v_fmac_f32_e32 v69, v67, v32
	v_fmac_f32_e32 v70, v66, v49
	v_fmac_f32_e32 v71, v67, v33
	v_fmac_f32_e32 v72, v66, v50
	v_fmac_f32_e32 v73, v67, v34
	v_fmac_f32_e32 v74, v66, v51
	v_fmac_f32_e32 v75, v67, v35
	v_fmac_f32_e32 v76, v66, v52
	v_fmac_f32_e32 v77, v67, v36
	v_fmac_f32_e32 v78, v66, v53
	v_fmac_f32_e32 v79, v67, v37
	v_fmac_f32_e32 v80, v66, v54
	v_fmac_f32_e32 v81, v67, v38
	v_fmac_f32_e32 v82, v66, v55
	v_fmac_f32_e32 v83, v67, v39
	v_fmac_f32_e32 v84, v66, v56
	v_fmac_f32_e32 v85, v67, v40
	v_fmac_f32_e32 v86, v66, v57
	v_fmac_f32_e32 v87, v67, v41
	v_fmac_f32_e32 v88, v66, v58
	v_fmac_f32_e32 v89, v67, v42
	v_fmac_f32_e32 v90, v66, v59
	v_fmac_f32_e32 v91, v67, v43
	v_fmac_f32_e32 v92, v66, v60
	v_fmac_f32_e32 v93, v67, v44
	v_fmac_f32_e32 v94, v66, v61
	v_fmac_f32_e32 v95, v67, v45
	v_fmac_f32_e32 v96, v66, v62
	v_fmac_f32_e32 v97, v67, v46
	v_fmac_f32_e32 v98, v66, v63
	v_fmac_f32_e32 v99, v67, v47
	s_add_u32 s14, s8, 0x1000
	s_addc_u32 s15, s9, 0
	global_store_dword v64, v68, s[14:15] offset:-4096
	global_store_dword v64, v69, s[14:15] offset:-3968
	global_store_dword v64, v70, s[14:15]
	global_store_dword v64, v71, s[14:15] offset:128
	s_add_u32 s14, s8, 0x3000
	s_addc_u32 s15, s9, 0
	global_store_dword v64, v72, s[14:15] offset:-4096
	global_store_dword v64, v73, s[14:15] offset:-3968
	global_store_dword v64, v74, s[14:15]
	global_store_dword v64, v75, s[14:15] offset:128
	s_add_u32 s14, s8, 0x9000
	s_addc_u32 s15, s9, 0
	global_store_dword v64, v76, s[14:15] offset:-4096
	global_store_dword v64, v77, s[14:15] offset:-3968
	global_store_dword v64, v78, s[14:15]
	global_store_dword v64, v79, s[14:15] offset:128
	s_add_u32 s14, s8, 0xb000
	s_addc_u32 s15, s9, 0
	global_store_dword v64, v80, s[14:15] offset:-4096
	global_store_dword v64, v81, s[14:15] offset:-3968
	global_store_dword v64, v82, s[14:15]
	global_store_dword v64, v83, s[14:15] offset:128
	s_add_u32 s14, s8, 0x11000
	s_addc_u32 s15, s9, 0
	global_store_dword v64, v84, s[14:15] offset:-4096
	global_store_dword v64, v85, s[14:15] offset:-3968
	global_store_dword v64, v86, s[14:15]
	global_store_dword v64, v87, s[14:15] offset:128
	s_add_u32 s14, s8, 0x13000
	s_addc_u32 s15, s9, 0
	global_store_dword v64, v88, s[14:15] offset:-4096
	global_store_dword v64, v89, s[14:15] offset:-3968
	global_store_dword v64, v90, s[14:15]
	global_store_dword v64, v91, s[14:15] offset:128
	s_add_u32 s14, s8, 0x19000
	s_addc_u32 s15, s9, 0
	global_store_dword v64, v92, s[14:15] offset:-4096
	global_store_dword v64, v93, s[14:15] offset:-3968
	global_store_dword v64, v94, s[14:15]
	global_store_dword v64, v95, s[14:15] offset:128
	s_add_u32 s14, s8, 0x1b000
	s_addc_u32 s15, s9, 0
	global_store_dword v64, v96, s[14:15] offset:-4096
	global_store_dword v64, v97, s[14:15] offset:-3968
	global_store_dword v64, v98, s[14:15]
	global_store_dword v64, v99, s[14:15] offset:128
	s_waitcnt vmcnt(32)
	v_fmac_f32_e32 v100, v66, v16
	v_fmac_f32_e32 v101, v67, v0
	v_fmac_f32_e32 v102, v66, v17
	v_fmac_f32_e32 v103, v67, v1
	v_fmac_f32_e32 v104, v66, v18
	v_fmac_f32_e32 v105, v67, v2
	v_fmac_f32_e32 v106, v66, v19
	v_fmac_f32_e32 v107, v67, v3
	v_fmac_f32_e32 v108, v66, v20
	v_fmac_f32_e32 v109, v67, v4
	v_fmac_f32_e32 v110, v66, v21
	v_fmac_f32_e32 v111, v67, v5
	v_fmac_f32_e32 v112, v66, v22
	v_fmac_f32_e32 v113, v67, v6
	v_fmac_f32_e32 v114, v66, v23
	v_fmac_f32_e32 v115, v67, v7
	v_fmac_f32_e32 v116, v66, v24
	v_fmac_f32_e32 v117, v67, v8
	v_fmac_f32_e32 v118, v66, v25
	v_fmac_f32_e32 v119, v67, v9
	v_fmac_f32_e32 v120, v66, v26
	v_fmac_f32_e32 v121, v67, v10
	v_fmac_f32_e32 v122, v66, v27
	v_fmac_f32_e32 v123, v67, v11
	v_fmac_f32_e32 v124, v66, v28
	v_fmac_f32_e32 v125, v67, v12
	v_fmac_f32_e32 v126, v66, v29
	v_fmac_f32_e32 v127, v67, v13
	v_fmac_f32_e32 v128, v66, v30
	v_fmac_f32_e32 v129, v67, v14
	v_fmac_f32_e32 v130, v66, v31
	v_fmac_f32_e32 v131, v67, v15
	s_add_u32 s14, s8, 0x21000
	s_addc_u32 s15, s9, 0
	global_store_dword v64, v100, s[14:15] offset:-4096
	global_store_dword v64, v101, s[14:15] offset:-3968
	global_store_dword v64, v102, s[14:15]
	global_store_dword v64, v103, s[14:15] offset:128
	s_add_u32 s14, s8, 0x23000
	s_addc_u32 s15, s9, 0
	global_store_dword v64, v104, s[14:15] offset:-4096
	global_store_dword v64, v105, s[14:15] offset:-3968
	global_store_dword v64, v106, s[14:15]
	global_store_dword v64, v107, s[14:15] offset:128
	s_add_u32 s14, s8, 0x29000
	s_addc_u32 s15, s9, 0
	global_store_dword v64, v108, s[14:15] offset:-4096
	global_store_dword v64, v109, s[14:15] offset:-3968
	global_store_dword v64, v110, s[14:15]
	global_store_dword v64, v111, s[14:15] offset:128
	s_add_u32 s14, s8, 0x2b000
	s_addc_u32 s15, s9, 0
	global_store_dword v64, v112, s[14:15] offset:-4096
	global_store_dword v64, v113, s[14:15] offset:-3968
	global_store_dword v64, v114, s[14:15]
	global_store_dword v64, v115, s[14:15] offset:128
	s_add_u32 s14, s8, 0x31000
	s_addc_u32 s15, s9, 0
	global_store_dword v64, v116, s[14:15] offset:-4096
	global_store_dword v64, v117, s[14:15] offset:-3968
	global_store_dword v64, v118, s[14:15]
	global_store_dword v64, v119, s[14:15] offset:128
	s_add_u32 s14, s8, 0x33000
	s_addc_u32 s15, s9, 0
	global_store_dword v64, v120, s[14:15] offset:-4096
	global_store_dword v64, v121, s[14:15] offset:-3968
	global_store_dword v64, v122, s[14:15]
	global_store_dword v64, v123, s[14:15] offset:128
	s_add_u32 s14, s8, 0x39000
	s_addc_u32 s15, s9, 0
	global_store_dword v64, v124, s[14:15] offset:-4096
	global_store_dword v64, v125, s[14:15] offset:-3968
	global_store_dword v64, v126, s[14:15]
	global_store_dword v64, v127, s[14:15] offset:128
	s_add_u32 s14, s8, 0x3b000
	s_addc_u32 s15, s9, 0
	global_store_dword v64, v128, s[14:15] offset:-4096
	global_store_dword v64, v129, s[14:15] offset:-3968
	global_store_dword v64, v130, s[14:15]
	global_store_dword v64, v131, s[14:15] offset:128
	s_branch .LBB0_1578

.LBB0_2253:
	s_waitcnt vmcnt(0)
	s_lshl_b32 s6, s5, 19
	s_lshl_b32 s7, s2, 9
	v_readfirstlane_b32 s2, v128
	v_readfirstlane_b32 s3, v129
	v_readlane_b32 s0, v255, 9
	s_add_u32 s8, s2, s56
	s_addc_u32 s9, s3, s57
	s_add_u32 s8, s8, s6
	s_addc_u32 s9, s9, 0
	s_add_u32 s8, s8, s7
	s_addc_u32 s9, s9, 0
	s_mov_b64 s[10:11], s[8:9]
	s_mul_i32 s12, s0, 0x12000
	s_add_u32 s12, s12, 0x2a25000
	s_sub_u32 s1, s5, 16
	s_lshr_b32 s1, s1, 4
	s_cmp_lt_u32 s5, 32
	s_cselect_b32 s1, 0, s1
	s_mul_i32 s1, s1, 0x6000
	s_add_u32 s12, s12, s1
	s_add_u32 s12, s12, s7
	s_add_u32 s12, s2, s12
	s_addc_u32 s13, s3, 0
	v_and_b32_e32 v64, 31, v231
	v_bfe_u32 v65, v231, 6, 1
	v_lshl_or_b32 v65, v65, 6, v64
	v_lshlrev_b32_e32 v65, 2, v65
	v_bfe_u32 v64, v231, 5, 1
	v_bfe_u32 v66, v231, 7, 1
	v_lshl_or_b32 v64, v66, 4, v64
	v_lshl_or_b32 v64, v64, 14, v65
	global_load_dword v66, v65, s[12:13]
	global_load_dword v67, v65, s[12:13] offset:128
	s_add_u32 s14, s10, 0x1000
	s_addc_u32 s15, s11, 0
	global_load_dword v68, v64, s[14:15] offset:-4096
	global_load_dword v69, v64, s[14:15] offset:-3968
	global_load_dword v70, v64, s[14:15]
	global_load_dword v71, v64, s[14:15] offset:128
	s_add_u32 s14, s10, 0x3000
	s_addc_u32 s15, s11, 0
	global_load_dword v72, v64, s[14:15] offset:-4096
	global_load_dword v73, v64, s[14:15] offset:-3968
	global_load_dword v74, v64, s[14:15]
	global_load_dword v75, v64, s[14:15] offset:128
	s_add_u32 s14, s10, 0x9000
	s_addc_u32 s15, s11, 0
	global_load_dword v76, v64, s[14:15] offset:-4096
	global_load_dword v77, v64, s[14:15] offset:-3968
	global_load_dword v78, v64, s[14:15]
	global_load_dword v79, v64, s[14:15] offset:128
	s_add_u32 s14, s10, 0xb000
	s_addc_u32 s15, s11, 0
	global_load_dword v80, v64, s[14:15] offset:-4096
	global_load_dword v81, v64, s[14:15] offset:-3968
	global_load_dword v82, v64, s[14:15]
	global_load_dword v83, v64, s[14:15] offset:128
	s_add_u32 s14, s10, 0x11000
	s_addc_u32 s15, s11, 0
	global_load_dword v84, v64, s[14:15] offset:-4096
	global_load_dword v85, v64, s[14:15] offset:-3968
	global_load_dword v86, v64, s[14:15]
	global_load_dword v87, v64, s[14:15] offset:128
	s_add_u32 s14, s10, 0x13000
	s_addc_u32 s15, s11, 0
	global_load_dword v88, v64, s[14:15] offset:-4096
	global_load_dword v89, v64, s[14:15] offset:-3968
	global_load_dword v90, v64, s[14:15]
	global_load_dword v91, v64, s[14:15] offset:128
	s_add_u32 s14, s10, 0x19000
	s_addc_u32 s15, s11, 0
	global_load_dword v92, v64, s[14:15] offset:-4096
	global_load_dword v93, v64, s[14:15] offset:-3968
	global_load_dword v94, v64, s[14:15]
	global_load_dword v95, v64, s[14:15] offset:128
	s_add_u32 s14, s10, 0x1b000
	s_addc_u32 s15, s11, 0
	global_load_dword v96, v64, s[14:15] offset:-4096
	global_load_dword v97, v64, s[14:15] offset:-3968
	global_load_dword v98, v64, s[14:15]
	global_load_dword v99, v64, s[14:15] offset:128
	s_add_u32 s14, s10, 0x21000
	s_addc_u32 s15, s11, 0
	global_load_dword v100, v64, s[14:15] offset:-4096
	global_load_dword v101, v64, s[14:15] offset:-3968
	global_load_dword v102, v64, s[14:15]
	global_load_dword v103, v64, s[14:15] offset:128
	s_add_u32 s14, s10, 0x23000
	s_addc_u32 s15, s11, 0
	global_load_dword v104, v64, s[14:15] offset:-4096
	global_load_dword v105, v64, s[14:15] offset:-3968
	global_load_dword v106, v64, s[14:15]
	global_load_dword v107, v64, s[14:15] offset:128
	s_add_u32 s14, s10, 0x29000
	s_addc_u32 s15, s11, 0
	global_load_dword v108, v64, s[14:15] offset:-4096
	global_load_dword v109, v64, s[14:15] offset:-3968
	global_load_dword v110, v64, s[14:15]
	global_load_dword v111, v64, s[14:15] offset:128
	s_add_u32 s14, s10, 0x2b000
	s_addc_u32 s15, s11, 0
	global_load_dword v112, v64, s[14:15] offset:-4096
	global_load_dword v113, v64, s[14:15] offset:-3968
	global_load_dword v114, v64, s[14:15]
	global_load_dword v115, v64, s[14:15] offset:128
	s_add_u32 s14, s10, 0x31000
	s_addc_u32 s15, s11, 0
	global_load_dword v116, v64, s[14:15] offset:-4096
	global_load_dword v117, v64, s[14:15] offset:-3968
	global_load_dword v118, v64, s[14:15]
	global_load_dword v119, v64, s[14:15] offset:128
	s_add_u32 s14, s10, 0x33000
	s_addc_u32 s15, s11, 0
	global_load_dword v120, v64, s[14:15] offset:-4096
	global_load_dword v121, v64, s[14:15] offset:-3968
	global_load_dword v122, v64, s[14:15]
	global_load_dword v123, v64, s[14:15] offset:128
	s_add_u32 s14, s10, 0x39000
	s_addc_u32 s15, s11, 0
	global_load_dword v124, v64, s[14:15] offset:-4096
	global_load_dword v125, v64, s[14:15] offset:-3968
	global_load_dword v126, v64, s[14:15]
	global_load_dword v127, v64, s[14:15] offset:128
	s_add_u32 s14, s10, 0x3b000
	s_addc_u32 s15, s11, 0
	global_load_dword v128, v64, s[14:15] offset:-4096
	global_load_dword v129, v64, s[14:15] offset:-3968
	global_load_dword v130, v64, s[14:15]
	global_load_dword v131, v64, s[14:15] offset:128
	s_waitcnt vmcnt(32)
	v_fmac_f32_e32 v68, v66, v48
	v_fmac_f32_e32 v69, v67, v32
	v_fmac_f32_e32 v70, v66, v49
	v_fmac_f32_e32 v71, v67, v33
	v_fmac_f32_e32 v72, v66, v50
	v_fmac_f32_e32 v73, v67, v34
	v_fmac_f32_e32 v74, v66, v51
	v_fmac_f32_e32 v75, v67, v35
	v_fmac_f32_e32 v76, v66, v52
	v_fmac_f32_e32 v77, v67, v36
	v_fmac_f32_e32 v78, v66, v53
	v_fmac_f32_e32 v79, v67, v37
	v_fmac_f32_e32 v80, v66, v54
	v_fmac_f32_e32 v81, v67, v38
	v_fmac_f32_e32 v82, v66, v55
	v_fmac_f32_e32 v83, v67, v39
	v_fmac_f32_e32 v84, v66, v56
	v_fmac_f32_e32 v85, v67, v40
	v_fmac_f32_e32 v86, v66, v57
	v_fmac_f32_e32 v87, v67, v41
	v_fmac_f32_e32 v88, v66, v58
	v_fmac_f32_e32 v89, v67, v42
	v_fmac_f32_e32 v90, v66, v59
	v_fmac_f32_e32 v91, v67, v43
	v_fmac_f32_e32 v92, v66, v60
	v_fmac_f32_e32 v93, v67, v44
	v_fmac_f32_e32 v94, v66, v61
	v_fmac_f32_e32 v95, v67, v45
	v_fmac_f32_e32 v96, v66, v62
	v_fmac_f32_e32 v97, v67, v46
	v_fmac_f32_e32 v98, v66, v63
	v_fmac_f32_e32 v99, v67, v47
	s_add_u32 s14, s8, 0x1000
	s_addc_u32 s15, s9, 0
	global_store_dword v64, v68, s[14:15] offset:-4096
	global_store_dword v64, v69, s[14:15] offset:-3968
	global_store_dword v64, v70, s[14:15]
	global_store_dword v64, v71, s[14:15] offset:128
	s_add_u32 s14, s8, 0x3000
	s_addc_u32 s15, s9, 0
	global_store_dword v64, v72, s[14:15] offset:-4096
	global_store_dword v64, v73, s[14:15] offset:-3968
	global_store_dword v64, v74, s[14:15]
	global_store_dword v64, v75, s[14:15] offset:128
	s_add_u32 s14, s8, 0x9000
	s_addc_u32 s15, s9, 0
	global_store_dword v64, v76, s[14:15] offset:-4096
	global_store_dword v64, v77, s[14:15] offset:-3968
	global_store_dword v64, v78, s[14:15]
	global_store_dword v64, v79, s[14:15] offset:128
	s_add_u32 s14, s8, 0xb000
	s_addc_u32 s15, s9, 0
	global_store_dword v64, v80, s[14:15] offset:-4096
	global_store_dword v64, v81, s[14:15] offset:-3968
	global_store_dword v64, v82, s[14:15]
	global_store_dword v64, v83, s[14:15] offset:128
	s_add_u32 s14, s8, 0x11000
	s_addc_u32 s15, s9, 0
	global_store_dword v64, v84, s[14:15] offset:-4096
	global_store_dword v64, v85, s[14:15] offset:-3968
	global_store_dword v64, v86, s[14:15]
	global_store_dword v64, v87, s[14:15] offset:128
	s_add_u32 s14, s8, 0x13000
	s_addc_u32 s15, s9, 0
	global_store_dword v64, v88, s[14:15] offset:-4096
	global_store_dword v64, v89, s[14:15] offset:-3968
	global_store_dword v64, v90, s[14:15]
	global_store_dword v64, v91, s[14:15] offset:128
	s_add_u32 s14, s8, 0x19000
	s_addc_u32 s15, s9, 0
	global_store_dword v64, v92, s[14:15] offset:-4096
	global_store_dword v64, v93, s[14:15] offset:-3968
	global_store_dword v64, v94, s[14:15]
	global_store_dword v64, v95, s[14:15] offset:128
	s_add_u32 s14, s8, 0x1b000
	s_addc_u32 s15, s9, 0
	global_store_dword v64, v96, s[14:15] offset:-4096
	global_store_dword v64, v97, s[14:15] offset:-3968
	global_store_dword v64, v98, s[14:15]
	global_store_dword v64, v99, s[14:15] offset:128
	s_waitcnt vmcnt(32)
	v_fmac_f32_e32 v100, v66, v16
	v_fmac_f32_e32 v101, v67, v0
	v_fmac_f32_e32 v102, v66, v17
	v_fmac_f32_e32 v103, v67, v1
	v_fmac_f32_e32 v104, v66, v18
	v_fmac_f32_e32 v105, v67, v2
	v_fmac_f32_e32 v106, v66, v19
	v_fmac_f32_e32 v107, v67, v3
	v_fmac_f32_e32 v108, v66, v20
	v_fmac_f32_e32 v109, v67, v4
	v_fmac_f32_e32 v110, v66, v21
	v_fmac_f32_e32 v111, v67, v5
	v_fmac_f32_e32 v112, v66, v22
	v_fmac_f32_e32 v113, v67, v6
	v_fmac_f32_e32 v114, v66, v23
	v_fmac_f32_e32 v115, v67, v7
	v_fmac_f32_e32 v116, v66, v24
	v_fmac_f32_e32 v117, v67, v8
	v_fmac_f32_e32 v118, v66, v25
	v_fmac_f32_e32 v119, v67, v9
	v_fmac_f32_e32 v120, v66, v26
	v_fmac_f32_e32 v121, v67, v10
	v_fmac_f32_e32 v122, v66, v27
	v_fmac_f32_e32 v123, v67, v11
	v_fmac_f32_e32 v124, v66, v28
	v_fmac_f32_e32 v125, v67, v12
	v_fmac_f32_e32 v126, v66, v29
	v_fmac_f32_e32 v127, v67, v13
	v_fmac_f32_e32 v128, v66, v30
	v_fmac_f32_e32 v129, v67, v14
	v_fmac_f32_e32 v130, v66, v31
	v_fmac_f32_e32 v131, v67, v15
	s_add_u32 s14, s8, 0x21000
	s_addc_u32 s15, s9, 0
	global_store_dword v64, v100, s[14:15] offset:-4096
	global_store_dword v64, v101, s[14:15] offset:-3968
	global_store_dword v64, v102, s[14:15]
	global_store_dword v64, v103, s[14:15] offset:128
	s_add_u32 s14, s8, 0x23000
	s_addc_u32 s15, s9, 0
	global_store_dword v64, v104, s[14:15] offset:-4096
	global_store_dword v64, v105, s[14:15] offset:-3968
	global_store_dword v64, v106, s[14:15]
	global_store_dword v64, v107, s[14:15] offset:128
	s_add_u32 s14, s8, 0x29000
	s_addc_u32 s15, s9, 0
	global_store_dword v64, v108, s[14:15] offset:-4096
	global_store_dword v64, v109, s[14:15] offset:-3968
	global_store_dword v64, v110, s[14:15]
	global_store_dword v64, v111, s[14:15] offset:128
	s_add_u32 s14, s8, 0x2b000
	s_addc_u32 s15, s9, 0
	global_store_dword v64, v112, s[14:15] offset:-4096
	global_store_dword v64, v113, s[14:15] offset:-3968
	global_store_dword v64, v114, s[14:15]
	global_store_dword v64, v115, s[14:15] offset:128
	s_add_u32 s14, s8, 0x31000
	s_addc_u32 s15, s9, 0
	global_store_dword v64, v116, s[14:15] offset:-4096
	global_store_dword v64, v117, s[14:15] offset:-3968
	global_store_dword v64, v118, s[14:15]
	global_store_dword v64, v119, s[14:15] offset:128
	s_add_u32 s14, s8, 0x33000
	s_addc_u32 s15, s9, 0
	global_store_dword v64, v120, s[14:15] offset:-4096
	global_store_dword v64, v121, s[14:15] offset:-3968
	global_store_dword v64, v122, s[14:15]
	global_store_dword v64, v123, s[14:15] offset:128
	s_add_u32 s14, s8, 0x39000
	s_addc_u32 s15, s9, 0
	global_store_dword v64, v124, s[14:15] offset:-4096
	global_store_dword v64, v125, s[14:15] offset:-3968
	global_store_dword v64, v126, s[14:15]
	global_store_dword v64, v127, s[14:15] offset:128
	s_add_u32 s14, s8, 0x3b000
	s_addc_u32 s15, s9, 0
	global_store_dword v64, v128, s[14:15] offset:-4096
	global_store_dword v64, v129, s[14:15] offset:-3968
	global_store_dword v64, v130, s[14:15]
	global_store_dword v64, v131, s[14:15] offset:128
	s_add_i32 s4, s4, 1
	s_mov_b64 s[2:3], 0
	s_barrier
